# prep step2 batched; norm1 bf16 loads batched; EpiGateRes epilogues (out-proj/FF2) load all 16 X pieces up front, no per-store drains
# speedup vs baseline: 1.0222x; 1.0118x over previous
.LBB0_82:
	v_lshl_add_u32 v172, s18, 8, v159
	v_lshl_or_b32 v122, s44, 8, v177
	v_ashrrev_i32_e32 v173, 31, v172
	v_ashrrev_i32_e32 v123, 31, v122
	v_lshlrev_b64 v[124:125], 11, v[172:173]
	v_lshl_add_u64 v[124:125], s[4:5], 0, v[124:125]
	v_lshlrev_b64 v[174:175], 1, v[122:123]
	s_ashr_i32 s11, s18, 4
	v_lshl_add_u64 v[154:155], v[124:125], 0, v[174:175]
	s_mul_hi_i32 s13, s11, 0x6000
	s_mulk_i32 s11, 0x6000
	s_add_u32 s20, s38, s11
	s_addc_u32 s21, s39, s13
	v_lshl_add_u64 v[122:123], v[122:123], 2, s[20:21]
	global_load_dwordx4 v[134:137], v[122:123], off
	global_load_dwordx4 v[130:133], v[122:123], off offset:16
	global_load_dwordx4 v[126:129], v[122:123], off offset:512
	s_nop 0
	global_load_dwordx4 v[122:125], v[122:123], off offset:528
	v_mov_b64_e32 v[172:173], v[154:155]
	v_mov_b64_e32 v[174:175], v[172:173]
	global_load_dwordx4 v[146:149], v[174:175], off
	global_load_dwordx4 v[154:157], v[174:175], off offset:256
	s_mov_b32 s20, 0x8000
	s_mov_b32 s21, 0
	v_lshl_add_u64 v[174:175], v[172:173], 0, s[20:21]
	global_load_dwordx4 v[180:183], v[174:175], off
	global_load_dwordx4 v[184:187], v[174:175], off offset:256
	s_mov_b32 s20, 0x10000
	s_mov_b32 s21, 0
	v_lshl_add_u64 v[174:175], v[172:173], 0, s[20:21]
	global_load_dwordx4 v[188:191], v[174:175], off
	global_load_dwordx4 v[192:195], v[174:175], off offset:256
	s_mov_b32 s20, 0x18000
	s_mov_b32 s21, 0
	v_lshl_add_u64 v[174:175], v[172:173], 0, s[20:21]
	global_load_dwordx4 v[196:199], v[174:175], off
	global_load_dwordx4 v[200:203], v[174:175], off offset:256
	s_mov_b32 s20, 0x40000
	s_mov_b32 s21, 0
	v_lshl_add_u64 v[174:175], v[172:173], 0, s[20:21]
	global_load_dwordx4 v[204:207], v[174:175], off
	global_load_dwordx4 v[208:211], v[174:175], off offset:256
	s_mov_b32 s20, 0x48000
	s_mov_b32 s21, 0
	v_lshl_add_u64 v[174:175], v[172:173], 0, s[20:21]
	global_load_dwordx4 v[222:225], v[174:175], off
	global_load_dwordx4 v[226:229], v[174:175], off offset:256
	s_mov_b32 s20, 0x50000
	s_mov_b32 s21, 0
	v_lshl_add_u64 v[174:175], v[172:173], 0, s[20:21]
	global_load_dwordx4 v[230:233], v[174:175], off
	global_load_dwordx4 v[234:237], v[174:175], off offset:256
	s_mov_b32 s20, 0x58000
	s_mov_b32 s21, 0
	v_lshl_add_u64 v[174:175], v[172:173], 0, s[20:21]
	global_load_dwordx4 v[240:243], v[174:175], off
	global_load_dwordx4 v[244:247], v[174:175], off offset:256
	v_mov_b64_e32 v[174:175], v[172:173]
	s_waitcnt vmcnt(14)
	v_lshlrev_b32_e32 v212, 16, v146
	v_and_b32_e32 v213, 0xffff0000, v146
	v_lshlrev_b32_e32 v248, 16, v148
	v_and_b32_e32 v249, 0xffff0000, v148
	v_lshlrev_b32_e32 v146, 16, v147
	v_and_b32_e32 v147, 0xffff0000, v147
	v_lshlrev_b32_e32 v148, 16, v149
	v_and_b32_e32 v149, 0xffff0000, v149
	v_pk_fma_f32 v[142:143], v[142:143], v[134:135], v[212:213]
	v_pk_fma_f32 v[138:139], v[138:139], v[130:131], v[248:249]
	v_pk_fma_f32 v[144:145], v[144:145], v[136:137], v[146:147]
	v_pk_fma_f32 v[140:141], v[140:141], v[132:133], v[148:149]
	v_cvt_pk_bf16_f32 v146, v142, v143
	v_cvt_pk_bf16_f32 v147, v144, v145
	v_cvt_pk_bf16_f32 v148, v138, v139
	v_cvt_pk_bf16_f32 v149, v140, v141
	global_store_dwordx4 v[174:175], v[146:149], off
	v_lshlrev_b32_e32 v212, 16, v154
	v_and_b32_e32 v213, 0xffff0000, v154
	v_lshlrev_b32_e32 v248, 16, v156
	v_and_b32_e32 v249, 0xffff0000, v156
	v_lshlrev_b32_e32 v154, 16, v155
	v_and_b32_e32 v155, 0xffff0000, v155
	v_lshlrev_b32_e32 v156, 16, v157
	v_and_b32_e32 v157, 0xffff0000, v157
	v_pk_fma_f32 v[114:115], v[114:115], v[126:127], v[212:213]
	v_pk_fma_f32 v[110:111], v[110:111], v[122:123], v[248:249]
	v_pk_fma_f32 v[116:117], v[116:117], v[128:129], v[154:155]
	v_pk_fma_f32 v[112:113], v[112:113], v[124:125], v[156:157]
	v_cvt_pk_bf16_f32 v154, v114, v115
	v_cvt_pk_bf16_f32 v155, v116, v117
	v_cvt_pk_bf16_f32 v156, v110, v111
	v_cvt_pk_bf16_f32 v157, v112, v113
	global_store_dwordx4 v[174:175], v[154:157], off offset:256
	s_mov_b32 s20, 0x8000
	s_mov_b32 s21, 0
	v_lshl_add_u64 v[174:175], v[172:173], 0, s[20:21]
	s_waitcnt vmcnt(14)
	v_lshlrev_b32_e32 v212, 16, v180
	v_and_b32_e32 v213, 0xffff0000, v180
	v_lshlrev_b32_e32 v248, 16, v182
	v_and_b32_e32 v249, 0xffff0000, v182
	v_lshlrev_b32_e32 v180, 16, v181
	v_and_b32_e32 v181, 0xffff0000, v181
	v_lshlrev_b32_e32 v182, 16, v183
	v_and_b32_e32 v183, 0xffff0000, v183
	v_pk_fma_f32 v[118:119], v[118:119], v[134:135], v[212:213]
	v_pk_fma_f32 v[106:107], v[106:107], v[130:131], v[248:249]
	v_pk_fma_f32 v[120:121], v[120:121], v[136:137], v[180:181]
	v_pk_fma_f32 v[108:109], v[108:109], v[132:133], v[182:183]
	v_cvt_pk_bf16_f32 v180, v118, v119
	v_cvt_pk_bf16_f32 v181, v120, v121
	v_cvt_pk_bf16_f32 v182, v106, v107
	v_cvt_pk_bf16_f32 v183, v108, v109
	global_store_dwordx4 v[174:175], v[180:183], off
	v_lshlrev_b32_e32 v212, 16, v184
	v_and_b32_e32 v213, 0xffff0000, v184
	v_lshlrev_b32_e32 v248, 16, v186
	v_and_b32_e32 v249, 0xffff0000, v186
	v_lshlrev_b32_e32 v184, 16, v185
	v_and_b32_e32 v185, 0xffff0000, v185
	v_lshlrev_b32_e32 v186, 16, v187
	v_and_b32_e32 v187, 0xffff0000, v187
	v_pk_fma_f32 v[102:103], v[102:103], v[126:127], v[212:213]
	v_pk_fma_f32 v[94:95], v[94:95], v[122:123], v[248:249]
	v_pk_fma_f32 v[104:105], v[104:105], v[128:129], v[184:185]
	v_pk_fma_f32 v[96:97], v[96:97], v[124:125], v[186:187]
	v_cvt_pk_bf16_f32 v184, v102, v103
	v_cvt_pk_bf16_f32 v185, v104, v105
	v_cvt_pk_bf16_f32 v186, v94, v95
	v_cvt_pk_bf16_f32 v187, v96, v97
	global_store_dwordx4 v[174:175], v[184:187], off offset:256
	s_mov_b32 s20, 0x10000
	s_mov_b32 s21, 0
	v_lshl_add_u64 v[174:175], v[172:173], 0, s[20:21]
	s_waitcnt vmcnt(14)
	v_lshlrev_b32_e32 v212, 16, v188
	v_and_b32_e32 v213, 0xffff0000, v188
	v_lshlrev_b32_e32 v248, 16, v190
	v_and_b32_e32 v249, 0xffff0000, v190
	v_lshlrev_b32_e32 v188, 16, v189
	v_and_b32_e32 v189, 0xffff0000, v189
	v_lshlrev_b32_e32 v190, 16, v191
	v_and_b32_e32 v191, 0xffff0000, v191
	v_pk_fma_f32 v[98:99], v[98:99], v[134:135], v[212:213]
	v_pk_fma_f32 v[90:91], v[90:91], v[130:131], v[248:249]
	v_pk_fma_f32 v[100:101], v[100:101], v[136:137], v[188:189]
	v_pk_fma_f32 v[92:93], v[92:93], v[132:133], v[190:191]
	v_cvt_pk_bf16_f32 v188, v98, v99
	v_cvt_pk_bf16_f32 v189, v100, v101
	v_cvt_pk_bf16_f32 v190, v90, v91
	v_cvt_pk_bf16_f32 v191, v92, v93
	global_store_dwordx4 v[174:175], v[188:191], off
	v_lshlrev_b32_e32 v212, 16, v192
	v_and_b32_e32 v213, 0xffff0000, v192
	v_lshlrev_b32_e32 v248, 16, v194
	v_and_b32_e32 v249, 0xffff0000, v194
	v_lshlrev_b32_e32 v192, 16, v193
	v_and_b32_e32 v193, 0xffff0000, v193
	v_lshlrev_b32_e32 v194, 16, v195
	v_and_b32_e32 v195, 0xffff0000, v195
	v_pk_fma_f32 v[82:83], v[82:83], v[126:127], v[212:213]
	v_pk_fma_f32 v[78:79], v[78:79], v[122:123], v[248:249]
	v_pk_fma_f32 v[84:85], v[84:85], v[128:129], v[192:193]
	v_pk_fma_f32 v[80:81], v[80:81], v[124:125], v[194:195]
	v_cvt_pk_bf16_f32 v192, v82, v83
	v_cvt_pk_bf16_f32 v193, v84, v85
	v_cvt_pk_bf16_f32 v194, v78, v79
	v_cvt_pk_bf16_f32 v195, v80, v81
	global_store_dwordx4 v[174:175], v[192:195], off offset:256
	s_mov_b32 s20, 0x18000
	s_mov_b32 s21, 0
	v_lshl_add_u64 v[174:175], v[172:173], 0, s[20:21]
	s_waitcnt vmcnt(14)
	v_lshlrev_b32_e32 v212, 16, v196
	v_and_b32_e32 v213, 0xffff0000, v196
	v_lshlrev_b32_e32 v248, 16, v198
	v_and_b32_e32 v249, 0xffff0000, v198
	v_lshlrev_b32_e32 v196, 16, v197
	v_and_b32_e32 v197, 0xffff0000, v197
	v_lshlrev_b32_e32 v198, 16, v199
	v_and_b32_e32 v199, 0xffff0000, v199
	v_pk_fma_f32 v[86:87], v[86:87], v[134:135], v[212:213]
	v_pk_fma_f32 v[74:75], v[74:75], v[130:131], v[248:249]
	v_pk_fma_f32 v[88:89], v[88:89], v[136:137], v[196:197]
	v_pk_fma_f32 v[76:77], v[76:77], v[132:133], v[198:199]
	v_cvt_pk_bf16_f32 v196, v86, v87
	v_cvt_pk_bf16_f32 v197, v88, v89
	v_cvt_pk_bf16_f32 v198, v74, v75
	v_cvt_pk_bf16_f32 v199, v76, v77
	global_store_dwordx4 v[174:175], v[196:199], off
	v_lshlrev_b32_e32 v212, 16, v200
	v_and_b32_e32 v213, 0xffff0000, v200
	v_lshlrev_b32_e32 v248, 16, v202
	v_and_b32_e32 v249, 0xffff0000, v202
	v_lshlrev_b32_e32 v200, 16, v201
	v_and_b32_e32 v201, 0xffff0000, v201
	v_lshlrev_b32_e32 v202, 16, v203
	v_and_b32_e32 v203, 0xffff0000, v203
	v_pk_fma_f32 v[70:71], v[70:71], v[126:127], v[212:213]
	v_pk_fma_f32 v[66:67], v[66:67], v[122:123], v[248:249]
	v_pk_fma_f32 v[72:73], v[72:73], v[128:129], v[200:201]
	v_pk_fma_f32 v[68:69], v[68:69], v[124:125], v[202:203]
	v_cvt_pk_bf16_f32 v200, v70, v71
	v_cvt_pk_bf16_f32 v201, v72, v73
	v_cvt_pk_bf16_f32 v202, v66, v67
	v_cvt_pk_bf16_f32 v203, v68, v69
	global_store_dwordx4 v[174:175], v[200:203], off offset:256
	s_mov_b32 s20, 0x40000
	s_mov_b32 s21, 0
	v_lshl_add_u64 v[174:175], v[172:173], 0, s[20:21]
	s_waitcnt vmcnt(14)
	v_lshlrev_b32_e32 v212, 16, v204
	v_and_b32_e32 v213, 0xffff0000, v204
	v_lshlrev_b32_e32 v248, 16, v206
	v_and_b32_e32 v249, 0xffff0000, v206
	v_lshlrev_b32_e32 v204, 16, v205
	v_and_b32_e32 v205, 0xffff0000, v205
	v_lshlrev_b32_e32 v206, 16, v207
	v_and_b32_e32 v207, 0xffff0000, v207
	v_pk_fma_f32 v[62:63], v[62:63], v[134:135], v[212:213]
	v_pk_fma_f32 v[58:59], v[58:59], v[130:131], v[248:249]
	v_pk_fma_f32 v[64:65], v[64:65], v[136:137], v[204:205]
	v_pk_fma_f32 v[60:61], v[60:61], v[132:133], v[206:207]
	v_cvt_pk_bf16_f32 v204, v62, v63
	v_cvt_pk_bf16_f32 v205, v64, v65
	v_cvt_pk_bf16_f32 v206, v58, v59
	v_cvt_pk_bf16_f32 v207, v60, v61
	global_store_dwordx4 v[174:175], v[204:207], off
	v_lshlrev_b32_e32 v212, 16, v208
	v_and_b32_e32 v213, 0xffff0000, v208
	v_lshlrev_b32_e32 v248, 16, v210
	v_and_b32_e32 v249, 0xffff0000, v210
	v_lshlrev_b32_e32 v208, 16, v209
	v_and_b32_e32 v209, 0xffff0000, v209
	v_lshlrev_b32_e32 v210, 16, v211
	v_and_b32_e32 v211, 0xffff0000, v211
	v_pk_fma_f32 v[50:51], v[50:51], v[126:127], v[212:213]
	v_pk_fma_f32 v[46:47], v[46:47], v[122:123], v[248:249]
	v_pk_fma_f32 v[52:53], v[52:53], v[128:129], v[208:209]
	v_pk_fma_f32 v[48:49], v[48:49], v[124:125], v[210:211]
	v_cvt_pk_bf16_f32 v208, v50, v51
	v_cvt_pk_bf16_f32 v209, v52, v53
	v_cvt_pk_bf16_f32 v210, v46, v47
	v_cvt_pk_bf16_f32 v211, v48, v49
	global_store_dwordx4 v[174:175], v[208:211], off offset:256
	s_mov_b32 s20, 0x48000
	s_mov_b32 s21, 0
	v_lshl_add_u64 v[174:175], v[172:173], 0, s[20:21]
	s_waitcnt vmcnt(14)
	v_lshlrev_b32_e32 v212, 16, v222
	v_and_b32_e32 v213, 0xffff0000, v222
	v_lshlrev_b32_e32 v248, 16, v224
	v_and_b32_e32 v249, 0xffff0000, v224
	v_lshlrev_b32_e32 v222, 16, v223
	v_and_b32_e32 v223, 0xffff0000, v223
	v_lshlrev_b32_e32 v224, 16, v225
	v_and_b32_e32 v225, 0xffff0000, v225
	v_pk_fma_f32 v[54:55], v[54:55], v[134:135], v[212:213]
	v_pk_fma_f32 v[42:43], v[42:43], v[130:131], v[248:249]
	v_pk_fma_f32 v[56:57], v[56:57], v[136:137], v[222:223]
	v_pk_fma_f32 v[44:45], v[44:45], v[132:133], v[224:225]
	v_cvt_pk_bf16_f32 v222, v54, v55
	v_cvt_pk_bf16_f32 v223, v56, v57
	v_cvt_pk_bf16_f32 v224, v42, v43
	v_cvt_pk_bf16_f32 v225, v44, v45
	global_store_dwordx4 v[174:175], v[222:225], off
	v_lshlrev_b32_e32 v212, 16, v226
	v_and_b32_e32 v213, 0xffff0000, v226
	v_lshlrev_b32_e32 v248, 16, v228
	v_and_b32_e32 v249, 0xffff0000, v228
	v_lshlrev_b32_e32 v226, 16, v227
	v_and_b32_e32 v227, 0xffff0000, v227
	v_lshlrev_b32_e32 v228, 16, v229
	v_and_b32_e32 v229, 0xffff0000, v229
	v_pk_fma_f32 v[38:39], v[38:39], v[126:127], v[212:213]
	v_pk_fma_f32 v[30:31], v[30:31], v[122:123], v[248:249]
	v_pk_fma_f32 v[40:41], v[40:41], v[128:129], v[226:227]
	v_pk_fma_f32 v[32:33], v[32:33], v[124:125], v[228:229]
	v_cvt_pk_bf16_f32 v226, v38, v39
	v_cvt_pk_bf16_f32 v227, v40, v41
	v_cvt_pk_bf16_f32 v228, v30, v31
	v_cvt_pk_bf16_f32 v229, v32, v33
	global_store_dwordx4 v[174:175], v[226:229], off offset:256
	s_mov_b32 s20, 0x50000
	s_mov_b32 s21, 0
	v_lshl_add_u64 v[174:175], v[172:173], 0, s[20:21]
	s_waitcnt vmcnt(14)
	v_lshlrev_b32_e32 v212, 16, v230
	v_and_b32_e32 v213, 0xffff0000, v230
	v_lshlrev_b32_e32 v248, 16, v232
	v_and_b32_e32 v249, 0xffff0000, v232
	v_lshlrev_b32_e32 v230, 16, v231
	v_and_b32_e32 v231, 0xffff0000, v231
	v_lshlrev_b32_e32 v232, 16, v233
	v_and_b32_e32 v233, 0xffff0000, v233
	v_pk_fma_f32 v[34:35], v[34:35], v[134:135], v[212:213]
	v_pk_fma_f32 v[26:27], v[26:27], v[130:131], v[248:249]
	v_pk_fma_f32 v[36:37], v[36:37], v[136:137], v[230:231]
	v_pk_fma_f32 v[28:29], v[28:29], v[132:133], v[232:233]
	v_cvt_pk_bf16_f32 v230, v34, v35
	v_cvt_pk_bf16_f32 v231, v36, v37
	v_cvt_pk_bf16_f32 v232, v26, v27
	v_cvt_pk_bf16_f32 v233, v28, v29
	global_store_dwordx4 v[174:175], v[230:233], off
	v_lshlrev_b32_e32 v212, 16, v234
	v_and_b32_e32 v213, 0xffff0000, v234
	v_lshlrev_b32_e32 v248, 16, v236
	v_and_b32_e32 v249, 0xffff0000, v236
	v_lshlrev_b32_e32 v234, 16, v235
	v_and_b32_e32 v235, 0xffff0000, v235
	v_lshlrev_b32_e32 v236, 16, v237
	v_and_b32_e32 v237, 0xffff0000, v237
	v_pk_fma_f32 v[18:19], v[18:19], v[126:127], v[212:213]
	v_pk_fma_f32 v[14:15], v[14:15], v[122:123], v[248:249]
	v_pk_fma_f32 v[20:21], v[20:21], v[128:129], v[234:235]
	v_pk_fma_f32 v[16:17], v[16:17], v[124:125], v[236:237]
	v_cvt_pk_bf16_f32 v234, v18, v19
	v_cvt_pk_bf16_f32 v235, v20, v21
	v_cvt_pk_bf16_f32 v236, v14, v15
	v_cvt_pk_bf16_f32 v237, v16, v17
	global_store_dwordx4 v[174:175], v[234:237], off offset:256
	s_mov_b32 s20, 0x58000
	s_mov_b32 s21, 0
	v_lshl_add_u64 v[174:175], v[172:173], 0, s[20:21]
	s_waitcnt vmcnt(14)
	v_lshlrev_b32_e32 v212, 16, v240
	v_and_b32_e32 v213, 0xffff0000, v240
	v_lshlrev_b32_e32 v248, 16, v242
	v_and_b32_e32 v249, 0xffff0000, v242
	v_lshlrev_b32_e32 v240, 16, v241
	v_and_b32_e32 v241, 0xffff0000, v241
	v_lshlrev_b32_e32 v242, 16, v243
	v_and_b32_e32 v243, 0xffff0000, v243
	v_pk_fma_f32 v[22:23], v[22:23], v[134:135], v[212:213]
	v_pk_fma_f32 v[10:11], v[10:11], v[130:131], v[248:249]
	v_pk_fma_f32 v[24:25], v[24:25], v[136:137], v[240:241]
	v_pk_fma_f32 v[12:13], v[12:13], v[132:133], v[242:243]
	v_cvt_pk_bf16_f32 v240, v22, v23
	v_cvt_pk_bf16_f32 v241, v24, v25
	v_cvt_pk_bf16_f32 v242, v10, v11
	v_cvt_pk_bf16_f32 v243, v12, v13
	global_store_dwordx4 v[174:175], v[240:243], off
	v_lshlrev_b32_e32 v212, 16, v244
	v_and_b32_e32 v213, 0xffff0000, v244
	v_lshlrev_b32_e32 v248, 16, v246
	v_and_b32_e32 v249, 0xffff0000, v246
	v_lshlrev_b32_e32 v244, 16, v245
	v_and_b32_e32 v245, 0xffff0000, v245
	v_lshlrev_b32_e32 v246, 16, v247
	v_and_b32_e32 v247, 0xffff0000, v247
	v_pk_fma_f32 v[6:7], v[6:7], v[126:127], v[212:213]
	v_pk_fma_f32 v[2:3], v[2:3], v[122:123], v[248:249]
	v_pk_fma_f32 v[8:9], v[8:9], v[128:129], v[244:245]
	v_pk_fma_f32 v[4:5], v[4:5], v[124:125], v[246:247]
	v_cvt_pk_bf16_f32 v244, v6, v7
	v_cvt_pk_bf16_f32 v245, v8, v9
	v_cvt_pk_bf16_f32 v246, v2, v3
	v_cvt_pk_bf16_f32 v247, v4, v5
	global_store_dwordx4 v[174:175], v[244:247], off offset:256
	s_andn2_b64 vcc, exec, s[0:1]
	s_mov_b64 s[0:1], -1
	s_movk_i32 s55, 0xf000
	s_mov_b32 s98, 1
	s_cbranch_vccnz .LBB0_71
	s_andn2_b64 vcc, exec, s[6:7]
	s_cbranch_vccnz .LBB0_70
	s_barrier
	s_branch .LBB0_70

.LBB0_218:
	s_or_b64 exec, exec, s[0:1]
	s_waitcnt lgkmcnt(0)
	s_barrier
	v_add_u32_e32 v13, s88, v234
	v_add_u32_e32 v13, 0x21600, v13
	v_add_u32_e32 v11, v234, v233
	v_add_u32_e32 v14, v234, v232
	ds_read_b128 v[16:19], v13 offset:256
	ds_read_b128 v[20:23], v13 offset:272
	ds_read_b128 v[24:27], v13 offset:512
	ds_read_b128 v[28:31], v13 offset:528
	ds_read_b128 v[32:35], v13 offset:0
	ds_read_b128 v[36:39], v13 offset:16
	ds_read_b64 v[40:41], v11 offset:0
	ds_read_b64 v[42:43], v11 offset:528
	ds_read_b64 v[44:45], v11 offset:1056
	ds_read_b64 v[46:47], v11 offset:1584
	ds_read_b64 v[48:49], v11 offset:2112
	ds_read_b64 v[50:51], v11 offset:2640
	ds_read_b64 v[52:53], v11 offset:3168
	ds_read_b64 v[54:55], v11 offset:3696
	ds_read_b64 v[56:57], v11 offset:33792
	ds_read_b64 v[58:59], v11 offset:34320
	ds_read_b64 v[60:61], v11 offset:34848
	ds_read_b64 v[62:63], v11 offset:35376
	ds_read_b64 v[64:65], v11 offset:35904
	ds_read_b64 v[66:67], v11 offset:36432
	ds_read_b64 v[68:69], v11 offset:36960
	ds_read_b64 v[70:71], v11 offset:37488
	v_add_u32_e32 v9, 0x18c00, v14
	v_add_u32_e32 v10, 0x1d000, v14
	s_mov_b32 s29, 0x15c00000
	v_add_co_u32_e32 v4, vcc, s29, v122
	s_nop 1
	v_addc_co_u32_e32 v5, vcc, 0, v123, vcc
	s_waitcnt lgkmcnt(15)
	v_add_f32_e32 v16, 0x358637bd, v16
	v_add_f32_e32 v17, 0x358637bd, v17
	v_add_f32_e32 v18, 0x358637bd, v18
	v_add_f32_e32 v19, 0x358637bd, v19
	v_add_f32_e32 v20, 0x358637bd, v20
	v_add_f32_e32 v21, 0x358637bd, v21
	v_add_f32_e32 v22, 0x358637bd, v22
	v_add_f32_e32 v23, 0x358637bd, v23
	v_add_f32_e32 v24, 0x358637bd, v24
	v_add_f32_e32 v25, 0x358637bd, v25
	v_add_f32_e32 v26, 0x358637bd, v26
	v_add_f32_e32 v27, 0x358637bd, v27
	v_add_f32_e32 v28, 0x358637bd, v28
	v_add_f32_e32 v29, 0x358637bd, v29
	v_add_f32_e32 v30, 0x358637bd, v30
	v_add_f32_e32 v31, 0x358637bd, v31
	v_rsq_f32_e32 v16, v16
	v_rsq_f32_e32 v17, v17
	v_rsq_f32_e32 v18, v18
	v_rsq_f32_e32 v19, v19
	v_rsq_f32_e32 v20, v20
	v_rsq_f32_e32 v21, v21
	v_rsq_f32_e32 v22, v22
	v_rsq_f32_e32 v23, v23
	v_rsq_f32_e32 v24, v24
	v_rsq_f32_e32 v25, v25
	v_rsq_f32_e32 v26, v26
	v_rsq_f32_e32 v27, v27
	v_rsq_f32_e32 v28, v28
	v_rsq_f32_e32 v29, v29
	v_rsq_f32_e32 v30, v30
	v_rsq_f32_e32 v31, v31
	v_mul_f32_e32 v16, 0x3db504f3, v16
	v_mul_f32_e32 v17, 0x3db504f3, v17
	v_mul_f32_e32 v18, 0x3db504f3, v18
	v_mul_f32_e32 v19, 0x3db504f3, v19
	v_mul_f32_e32 v20, 0x3db504f3, v20
	v_mul_f32_e32 v21, 0x3db504f3, v21
	v_mul_f32_e32 v22, 0x3db504f3, v22
	v_mul_f32_e32 v23, 0x3db504f3, v23
	s_waitcnt lgkmcnt(7)
	v_mul_f32_e32 v40, v40, v16
	v_mul_f32_e32 v41, v41, v16
	v_mul_f32_e32 v56, v56, v24
	v_mul_f32_e32 v57, v57, v24
	v_cvt_pk_bf16_f32 v6, v40, v41
	v_cvt_pk_bf16_f32 v7, v56, v57
	v_mul_f32_e32 v40, v40, v32
	v_mul_f32_e32 v41, v41, v32
	ds_write_b32 v9, v6 offset:0
	ds_write_b32 v10, v7 offset:0
	ds_write_b64 v11, v[56:57] offset:33792
	v_cvt_pk_bf16_f32 v8, v40, v41
	global_store_dword v[4:5], v8, off offset:0
	s_waitcnt lgkmcnt(9)
	v_mul_f32_e32 v42, v42, v17
	v_mul_f32_e32 v43, v43, v17
	v_mul_f32_e32 v58, v58, v25
	v_mul_f32_e32 v59, v59, v25
	v_cvt_pk_bf16_f32 v6, v42, v43
	v_cvt_pk_bf16_f32 v7, v58, v59
	v_mul_f32_e32 v42, v42, v33
	v_mul_f32_e32 v43, v43, v33
	ds_write_b32 v9, v6 offset:272
	ds_write_b32 v10, v7 offset:272
	ds_write_b64 v11, v[58:59] offset:34320
	v_cvt_pk_bf16_f32 v8, v42, v43
	global_store_dword v[4:5], v8, off offset:256
	s_waitcnt lgkmcnt(11)
	v_mul_f32_e32 v44, v44, v18
	v_mul_f32_e32 v45, v45, v18
	v_mul_f32_e32 v60, v60, v26
	v_mul_f32_e32 v61, v61, v26
	v_cvt_pk_bf16_f32 v6, v44, v45
	v_cvt_pk_bf16_f32 v7, v60, v61
	v_mul_f32_e32 v44, v44, v34
	v_mul_f32_e32 v45, v45, v34
	ds_write_b32 v9, v6 offset:544
	ds_write_b32 v10, v7 offset:544
	ds_write_b64 v11, v[60:61] offset:34848
	v_cvt_pk_bf16_f32 v8, v44, v45
	global_store_dword v[4:5], v8, off offset:512
	s_waitcnt lgkmcnt(13)
	v_mul_f32_e32 v46, v46, v19
	v_mul_f32_e32 v47, v47, v19
	v_mul_f32_e32 v62, v62, v27
	v_mul_f32_e32 v63, v63, v27
	v_cvt_pk_bf16_f32 v6, v46, v47
	v_cvt_pk_bf16_f32 v7, v62, v63
	v_mul_f32_e32 v46, v46, v35
	v_mul_f32_e32 v47, v47, v35
	ds_write_b32 v9, v6 offset:816
	ds_write_b32 v10, v7 offset:816
	ds_write_b64 v11, v[62:63] offset:35376
	v_cvt_pk_bf16_f32 v8, v46, v47
	global_store_dword v[4:5], v8, off offset:768
	s_waitcnt lgkmcnt(15)
	v_mul_f32_e32 v48, v48, v20
	v_mul_f32_e32 v49, v49, v20
	v_mul_f32_e32 v64, v64, v28
	v_mul_f32_e32 v65, v65, v28
	v_cvt_pk_bf16_f32 v6, v48, v49
	v_cvt_pk_bf16_f32 v7, v64, v65
	v_mul_f32_e32 v48, v48, v36
	v_mul_f32_e32 v49, v49, v36
	ds_write_b32 v9, v6 offset:1088
	ds_write_b32 v10, v7 offset:1088
	ds_write_b64 v11, v[64:65] offset:35904
	v_cvt_pk_bf16_f32 v8, v48, v49
	global_store_dword v[4:5], v8, off offset:1024
	s_waitcnt lgkmcnt(15)
	v_mul_f32_e32 v50, v50, v21
	v_mul_f32_e32 v51, v51, v21
	v_mul_f32_e32 v66, v66, v29
	v_mul_f32_e32 v67, v67, v29
	v_cvt_pk_bf16_f32 v6, v50, v51
	v_cvt_pk_bf16_f32 v7, v66, v67
	v_mul_f32_e32 v50, v50, v37
	v_mul_f32_e32 v51, v51, v37
	ds_write_b32 v9, v6 offset:1360
	ds_write_b32 v10, v7 offset:1360
	ds_write_b64 v11, v[66:67] offset:36432
	v_cvt_pk_bf16_f32 v8, v50, v51
	global_store_dword v[4:5], v8, off offset:1280
	v_mul_f32_e32 v52, v52, v22
	v_mul_f32_e32 v53, v53, v22
	v_mul_f32_e32 v68, v68, v30
	v_mul_f32_e32 v69, v69, v30
	v_cvt_pk_bf16_f32 v6, v52, v53
	v_cvt_pk_bf16_f32 v7, v68, v69
	v_mul_f32_e32 v52, v52, v38
	v_mul_f32_e32 v53, v53, v38
	ds_write_b32 v9, v6 offset:1632
	ds_write_b32 v10, v7 offset:1632
	ds_write_b64 v11, v[68:69] offset:36960
	v_cvt_pk_bf16_f32 v8, v52, v53
	global_store_dword v[4:5], v8, off offset:1536
	v_mul_f32_e32 v54, v54, v23
	v_mul_f32_e32 v55, v55, v23
	v_mul_f32_e32 v70, v70, v31
	v_mul_f32_e32 v71, v71, v31
	v_cvt_pk_bf16_f32 v6, v54, v55
	v_cvt_pk_bf16_f32 v7, v70, v71
	v_mul_f32_e32 v54, v54, v39
	v_mul_f32_e32 v55, v55, v39
	ds_write_b32 v9, v6 offset:1904
	ds_write_b32 v10, v7 offset:1904
	ds_write_b64 v11, v[70:71] offset:37488
	v_cvt_pk_bf16_f32 v8, v54, v55
	global_store_dword v[4:5], v8, off offset:1792
	s_add_i32 s28, s88, 32
	s_mov_b32 s1, 0
	s_movk_i32 s0, 0x800
	s_cmpk_eq_i32 s0, 0x800
	v_add_u32_e32 v28, 0x18c00, v234
	v_add_u32_e32 v18, 0x1d000, v234
	v_cndmask_b32_e64 v2, v28, v18, s[44:45]
	v_add_u32_e32 v33, v18, v180
	s_waitcnt lgkmcnt(0)
	s_barrier
	v_add3_u32 v2, v2, v179, v180
	v_add_u32_e32 v39, v33, v187
	ds_read_b128 v[14:17], v2
	ds_read_b128 v[10:13], v2 offset:64
	ds_read_b128 v[6:9], v2 offset:128
	ds_read_b128 v[2:5], v2 offset:192
	ds_read_b128 v[18:21], v39
	ds_read_b128 v[22:25], v39 offset:64
	s_waitcnt lgkmcnt(0)
	v_mfma_f32_16x16x32_bf16 v[18:21], v[14:17], v[18:21], 0
	v_lshl_add_u32 v29, v181, 2, v239
	s_ashr_i32 s65, s64, 31
	s_lshl_b64 s[68:69], s[64:65], 12
	v_mfma_f32_16x16x32_bf16 v[18:21], v[10:13], v[22:25], v[18:21]
	ds_read_b128 v[22:25], v39 offset:128
	s_mov_b64 s[0:1], -1
	s_and_b64 vcc, exec, s[60:61]
	s_waitcnt lgkmcnt(0)
	v_mfma_f32_16x16x32_bf16 v[18:21], v[6:9], v[22:25], v[18:21]
	ds_read_b128 v[22:25], v39 offset:192
	ds_read_b32 v34, v29 offset:256
	s_waitcnt lgkmcnt(0)
	v_mfma_f32_16x16x32_bf16 v[18:21], v[2:5], v[22:25], v[18:21]
	v_lshlrev_b32_e32 v23, 2, v178
	v_add_u32_e32 v22, v239, v23
	ds_read_b32 v22, v22 offset:256
	s_waitcnt lgkmcnt(0)
	v_sub_f32_e32 v24, v34, v22
	v_min_f32_e32 v24, 0, v24
	v_mul_f32_e32 v24, 0x3fb8aa3b, v24
	v_exp_f32_e32 v24, v24
	s_cbranch_vccz .LBB0_222
	v_mul_f32_e32 v25, v18, v24
	v_cvt_pk_bf16_f32 v25, v25, s0
	v_cndmask_b32_e64 v25, v25, 0, s[26:27]
	v_lshl_add_u64 v[26:27], s[68:69], 1, v[108:109]
	flat_store_short v[26:27], v25
	s_mov_b64 s[0:1], 0

.LBB0_384:
	v_lshl_add_u32 v172, s18, 8, v159
	v_lshl_or_b32 v122, s46, 8, v177
	v_ashrrev_i32_e32 v173, 31, v172
	v_ashrrev_i32_e32 v123, 31, v122
	v_lshlrev_b64 v[124:125], 11, v[172:173]
	v_lshl_add_u64 v[124:125], s[6:7], 0, v[124:125]
	v_lshlrev_b64 v[174:175], 1, v[122:123]
	s_ashr_i32 s11, s18, 4
	v_lshl_add_u64 v[154:155], v[124:125], 0, v[174:175]
	s_mul_hi_i32 s13, s11, 0x6000
	s_mulk_i32 s11, 0x6000
	s_add_u32 s20, s40, s11
	s_addc_u32 s21, s41, s13
	v_lshl_add_u64 v[122:123], v[122:123], 2, s[20:21]
	global_load_dwordx4 v[134:137], v[122:123], off
	global_load_dwordx4 v[130:133], v[122:123], off offset:16
	global_load_dwordx4 v[126:129], v[122:123], off offset:512
	s_nop 0
	global_load_dwordx4 v[122:125], v[122:123], off offset:528
	v_mov_b64_e32 v[172:173], v[154:155]
	v_mov_b64_e32 v[174:175], v[172:173]
	global_load_dwordx4 v[146:149], v[174:175], off
	global_load_dwordx4 v[154:157], v[174:175], off offset:256
	s_mov_b32 s20, 0x8000
	s_mov_b32 s21, 0
	v_lshl_add_u64 v[174:175], v[172:173], 0, s[20:21]
	global_load_dwordx4 v[180:183], v[174:175], off
	global_load_dwordx4 v[184:187], v[174:175], off offset:256
	s_mov_b32 s20, 0x10000
	s_mov_b32 s21, 0
	v_lshl_add_u64 v[174:175], v[172:173], 0, s[20:21]
	global_load_dwordx4 v[188:191], v[174:175], off
	global_load_dwordx4 v[192:195], v[174:175], off offset:256
	s_mov_b32 s20, 0x18000
	s_mov_b32 s21, 0
	v_lshl_add_u64 v[174:175], v[172:173], 0, s[20:21]
	global_load_dwordx4 v[196:199], v[174:175], off
	global_load_dwordx4 v[200:203], v[174:175], off offset:256
	s_mov_b32 s20, 0x40000
	s_mov_b32 s21, 0
	v_lshl_add_u64 v[174:175], v[172:173], 0, s[20:21]
	global_load_dwordx4 v[204:207], v[174:175], off
	global_load_dwordx4 v[208:211], v[174:175], off offset:256
	s_mov_b32 s20, 0x48000
	s_mov_b32 s21, 0
	v_lshl_add_u64 v[174:175], v[172:173], 0, s[20:21]
	global_load_dwordx4 v[222:225], v[174:175], off
	global_load_dwordx4 v[226:229], v[174:175], off offset:256
	s_mov_b32 s20, 0x50000
	s_mov_b32 s21, 0
	v_lshl_add_u64 v[174:175], v[172:173], 0, s[20:21]
	global_load_dwordx4 v[230:233], v[174:175], off
	global_load_dwordx4 v[234:237], v[174:175], off offset:256
	s_mov_b32 s20, 0x58000
	s_mov_b32 s21, 0
	v_lshl_add_u64 v[174:175], v[172:173], 0, s[20:21]
	global_load_dwordx4 v[240:243], v[174:175], off
	global_load_dwordx4 v[244:247], v[174:175], off offset:256
	v_mov_b64_e32 v[174:175], v[172:173]
	s_waitcnt vmcnt(14)
	v_lshlrev_b32_e32 v212, 16, v146
	v_and_b32_e32 v213, 0xffff0000, v146
	v_lshlrev_b32_e32 v248, 16, v148
	v_and_b32_e32 v249, 0xffff0000, v148
	v_lshlrev_b32_e32 v146, 16, v147
	v_and_b32_e32 v147, 0xffff0000, v147
	v_lshlrev_b32_e32 v148, 16, v149
	v_and_b32_e32 v149, 0xffff0000, v149
	v_pk_fma_f32 v[142:143], v[142:143], v[134:135], v[212:213]
	v_pk_fma_f32 v[138:139], v[138:139], v[130:131], v[248:249]
	v_pk_fma_f32 v[144:145], v[144:145], v[136:137], v[146:147]
	v_pk_fma_f32 v[140:141], v[140:141], v[132:133], v[148:149]
	v_cvt_pk_bf16_f32 v146, v142, v143
	v_cvt_pk_bf16_f32 v147, v144, v145
	v_cvt_pk_bf16_f32 v148, v138, v139
	v_cvt_pk_bf16_f32 v149, v140, v141
	global_store_dwordx4 v[174:175], v[146:149], off
	v_lshlrev_b32_e32 v212, 16, v154
	v_and_b32_e32 v213, 0xffff0000, v154
	v_lshlrev_b32_e32 v248, 16, v156
	v_and_b32_e32 v249, 0xffff0000, v156
	v_lshlrev_b32_e32 v154, 16, v155
	v_and_b32_e32 v155, 0xffff0000, v155
	v_lshlrev_b32_e32 v156, 16, v157
	v_and_b32_e32 v157, 0xffff0000, v157
	v_pk_fma_f32 v[114:115], v[114:115], v[126:127], v[212:213]
	v_pk_fma_f32 v[110:111], v[110:111], v[122:123], v[248:249]
	v_pk_fma_f32 v[116:117], v[116:117], v[128:129], v[154:155]
	v_pk_fma_f32 v[112:113], v[112:113], v[124:125], v[156:157]
	v_cvt_pk_bf16_f32 v154, v114, v115
	v_cvt_pk_bf16_f32 v155, v116, v117
	v_cvt_pk_bf16_f32 v156, v110, v111
	v_cvt_pk_bf16_f32 v157, v112, v113
	global_store_dwordx4 v[174:175], v[154:157], off offset:256
	s_mov_b32 s20, 0x8000
	s_mov_b32 s21, 0
	v_lshl_add_u64 v[174:175], v[172:173], 0, s[20:21]
	s_waitcnt vmcnt(14)
	v_lshlrev_b32_e32 v212, 16, v180
	v_and_b32_e32 v213, 0xffff0000, v180
	v_lshlrev_b32_e32 v248, 16, v182
	v_and_b32_e32 v249, 0xffff0000, v182
	v_lshlrev_b32_e32 v180, 16, v181
	v_and_b32_e32 v181, 0xffff0000, v181
	v_lshlrev_b32_e32 v182, 16, v183
	v_and_b32_e32 v183, 0xffff0000, v183
	v_pk_fma_f32 v[118:119], v[118:119], v[134:135], v[212:213]
	v_pk_fma_f32 v[106:107], v[106:107], v[130:131], v[248:249]
	v_pk_fma_f32 v[120:121], v[120:121], v[136:137], v[180:181]
	v_pk_fma_f32 v[108:109], v[108:109], v[132:133], v[182:183]
	v_cvt_pk_bf16_f32 v180, v118, v119
	v_cvt_pk_bf16_f32 v181, v120, v121
	v_cvt_pk_bf16_f32 v182, v106, v107
	v_cvt_pk_bf16_f32 v183, v108, v109
	global_store_dwordx4 v[174:175], v[180:183], off
	v_lshlrev_b32_e32 v212, 16, v184
	v_and_b32_e32 v213, 0xffff0000, v184
	v_lshlrev_b32_e32 v248, 16, v186
	v_and_b32_e32 v249, 0xffff0000, v186
	v_lshlrev_b32_e32 v184, 16, v185
	v_and_b32_e32 v185, 0xffff0000, v185
	v_lshlrev_b32_e32 v186, 16, v187
	v_and_b32_e32 v187, 0xffff0000, v187
	v_pk_fma_f32 v[102:103], v[102:103], v[126:127], v[212:213]
	v_pk_fma_f32 v[94:95], v[94:95], v[122:123], v[248:249]
	v_pk_fma_f32 v[104:105], v[104:105], v[128:129], v[184:185]
	v_pk_fma_f32 v[96:97], v[96:97], v[124:125], v[186:187]
	v_cvt_pk_bf16_f32 v184, v102, v103
	v_cvt_pk_bf16_f32 v185, v104, v105
	v_cvt_pk_bf16_f32 v186, v94, v95
	v_cvt_pk_bf16_f32 v187, v96, v97
	global_store_dwordx4 v[174:175], v[184:187], off offset:256
	s_mov_b32 s20, 0x10000
	s_mov_b32 s21, 0
	v_lshl_add_u64 v[174:175], v[172:173], 0, s[20:21]
	s_waitcnt vmcnt(14)
	v_lshlrev_b32_e32 v212, 16, v188
	v_and_b32_e32 v213, 0xffff0000, v188
	v_lshlrev_b32_e32 v248, 16, v190
	v_and_b32_e32 v249, 0xffff0000, v190
	v_lshlrev_b32_e32 v188, 16, v189
	v_and_b32_e32 v189, 0xffff0000, v189
	v_lshlrev_b32_e32 v190, 16, v191
	v_and_b32_e32 v191, 0xffff0000, v191
	v_pk_fma_f32 v[98:99], v[98:99], v[134:135], v[212:213]
	v_pk_fma_f32 v[90:91], v[90:91], v[130:131], v[248:249]
	v_pk_fma_f32 v[100:101], v[100:101], v[136:137], v[188:189]
	v_pk_fma_f32 v[92:93], v[92:93], v[132:133], v[190:191]
	v_cvt_pk_bf16_f32 v188, v98, v99
	v_cvt_pk_bf16_f32 v189, v100, v101
	v_cvt_pk_bf16_f32 v190, v90, v91
	v_cvt_pk_bf16_f32 v191, v92, v93
	global_store_dwordx4 v[174:175], v[188:191], off
	v_lshlrev_b32_e32 v212, 16, v192
	v_and_b32_e32 v213, 0xffff0000, v192
	v_lshlrev_b32_e32 v248, 16, v194
	v_and_b32_e32 v249, 0xffff0000, v194
	v_lshlrev_b32_e32 v192, 16, v193
	v_and_b32_e32 v193, 0xffff0000, v193
	v_lshlrev_b32_e32 v194, 16, v195
	v_and_b32_e32 v195, 0xffff0000, v195
	v_pk_fma_f32 v[82:83], v[82:83], v[126:127], v[212:213]
	v_pk_fma_f32 v[78:79], v[78:79], v[122:123], v[248:249]
	v_pk_fma_f32 v[84:85], v[84:85], v[128:129], v[192:193]
	v_pk_fma_f32 v[80:81], v[80:81], v[124:125], v[194:195]
	v_cvt_pk_bf16_f32 v192, v82, v83
	v_cvt_pk_bf16_f32 v193, v84, v85
	v_cvt_pk_bf16_f32 v194, v78, v79
	v_cvt_pk_bf16_f32 v195, v80, v81
	global_store_dwordx4 v[174:175], v[192:195], off offset:256
	s_mov_b32 s20, 0x18000
	s_mov_b32 s21, 0
	v_lshl_add_u64 v[174:175], v[172:173], 0, s[20:21]
	s_waitcnt vmcnt(14)
	v_lshlrev_b32_e32 v212, 16, v196
	v_and_b32_e32 v213, 0xffff0000, v196
	v_lshlrev_b32_e32 v248, 16, v198
	v_and_b32_e32 v249, 0xffff0000, v198
	v_lshlrev_b32_e32 v196, 16, v197
	v_and_b32_e32 v197, 0xffff0000, v197
	v_lshlrev_b32_e32 v198, 16, v199
	v_and_b32_e32 v199, 0xffff0000, v199
	v_pk_fma_f32 v[86:87], v[86:87], v[134:135], v[212:213]
	v_pk_fma_f32 v[74:75], v[74:75], v[130:131], v[248:249]
	v_pk_fma_f32 v[88:89], v[88:89], v[136:137], v[196:197]
	v_pk_fma_f32 v[76:77], v[76:77], v[132:133], v[198:199]
	v_cvt_pk_bf16_f32 v196, v86, v87
	v_cvt_pk_bf16_f32 v197, v88, v89
	v_cvt_pk_bf16_f32 v198, v74, v75
	v_cvt_pk_bf16_f32 v199, v76, v77
	global_store_dwordx4 v[174:175], v[196:199], off
	v_lshlrev_b32_e32 v212, 16, v200
	v_and_b32_e32 v213, 0xffff0000, v200
	v_lshlrev_b32_e32 v248, 16, v202
	v_and_b32_e32 v249, 0xffff0000, v202
	v_lshlrev_b32_e32 v200, 16, v201
	v_and_b32_e32 v201, 0xffff0000, v201
	v_lshlrev_b32_e32 v202, 16, v203
	v_and_b32_e32 v203, 0xffff0000, v203
	v_pk_fma_f32 v[70:71], v[70:71], v[126:127], v[212:213]
	v_pk_fma_f32 v[66:67], v[66:67], v[122:123], v[248:249]
	v_pk_fma_f32 v[72:73], v[72:73], v[128:129], v[200:201]
	v_pk_fma_f32 v[68:69], v[68:69], v[124:125], v[202:203]
	v_cvt_pk_bf16_f32 v200, v70, v71
	v_cvt_pk_bf16_f32 v201, v72, v73
	v_cvt_pk_bf16_f32 v202, v66, v67
	v_cvt_pk_bf16_f32 v203, v68, v69
	global_store_dwordx4 v[174:175], v[200:203], off offset:256
	s_mov_b32 s20, 0x40000
	s_mov_b32 s21, 0
	v_lshl_add_u64 v[174:175], v[172:173], 0, s[20:21]
	s_waitcnt vmcnt(14)
	v_lshlrev_b32_e32 v212, 16, v204
	v_and_b32_e32 v213, 0xffff0000, v204
	v_lshlrev_b32_e32 v248, 16, v206
	v_and_b32_e32 v249, 0xffff0000, v206
	v_lshlrev_b32_e32 v204, 16, v205
	v_and_b32_e32 v205, 0xffff0000, v205
	v_lshlrev_b32_e32 v206, 16, v207
	v_and_b32_e32 v207, 0xffff0000, v207
	v_pk_fma_f32 v[62:63], v[62:63], v[134:135], v[212:213]
	v_pk_fma_f32 v[58:59], v[58:59], v[130:131], v[248:249]
	v_pk_fma_f32 v[64:65], v[64:65], v[136:137], v[204:205]
	v_pk_fma_f32 v[60:61], v[60:61], v[132:133], v[206:207]
	v_cvt_pk_bf16_f32 v204, v62, v63
	v_cvt_pk_bf16_f32 v205, v64, v65
	v_cvt_pk_bf16_f32 v206, v58, v59
	v_cvt_pk_bf16_f32 v207, v60, v61
	global_store_dwordx4 v[174:175], v[204:207], off
	v_lshlrev_b32_e32 v212, 16, v208
	v_and_b32_e32 v213, 0xffff0000, v208
	v_lshlrev_b32_e32 v248, 16, v210
	v_and_b32_e32 v249, 0xffff0000, v210
	v_lshlrev_b32_e32 v208, 16, v209
	v_and_b32_e32 v209, 0xffff0000, v209
	v_lshlrev_b32_e32 v210, 16, v211
	v_and_b32_e32 v211, 0xffff0000, v211
	v_pk_fma_f32 v[50:51], v[50:51], v[126:127], v[212:213]
	v_pk_fma_f32 v[46:47], v[46:47], v[122:123], v[248:249]
	v_pk_fma_f32 v[52:53], v[52:53], v[128:129], v[208:209]
	v_pk_fma_f32 v[48:49], v[48:49], v[124:125], v[210:211]
	v_cvt_pk_bf16_f32 v208, v50, v51
	v_cvt_pk_bf16_f32 v209, v52, v53
	v_cvt_pk_bf16_f32 v210, v46, v47
	v_cvt_pk_bf16_f32 v211, v48, v49
	global_store_dwordx4 v[174:175], v[208:211], off offset:256
	s_mov_b32 s20, 0x48000
	s_mov_b32 s21, 0
	v_lshl_add_u64 v[174:175], v[172:173], 0, s[20:21]
	s_waitcnt vmcnt(14)
	v_lshlrev_b32_e32 v212, 16, v222
	v_and_b32_e32 v213, 0xffff0000, v222
	v_lshlrev_b32_e32 v248, 16, v224
	v_and_b32_e32 v249, 0xffff0000, v224
	v_lshlrev_b32_e32 v222, 16, v223
	v_and_b32_e32 v223, 0xffff0000, v223
	v_lshlrev_b32_e32 v224, 16, v225
	v_and_b32_e32 v225, 0xffff0000, v225
	v_pk_fma_f32 v[54:55], v[54:55], v[134:135], v[212:213]
	v_pk_fma_f32 v[42:43], v[42:43], v[130:131], v[248:249]
	v_pk_fma_f32 v[56:57], v[56:57], v[136:137], v[222:223]
	v_pk_fma_f32 v[44:45], v[44:45], v[132:133], v[224:225]
	v_cvt_pk_bf16_f32 v222, v54, v55
	v_cvt_pk_bf16_f32 v223, v56, v57
	v_cvt_pk_bf16_f32 v224, v42, v43
	v_cvt_pk_bf16_f32 v225, v44, v45
	global_store_dwordx4 v[174:175], v[222:225], off
	v_lshlrev_b32_e32 v212, 16, v226
	v_and_b32_e32 v213, 0xffff0000, v226
	v_lshlrev_b32_e32 v248, 16, v228
	v_and_b32_e32 v249, 0xffff0000, v228
	v_lshlrev_b32_e32 v226, 16, v227
	v_and_b32_e32 v227, 0xffff0000, v227
	v_lshlrev_b32_e32 v228, 16, v229
	v_and_b32_e32 v229, 0xffff0000, v229
	v_pk_fma_f32 v[38:39], v[38:39], v[126:127], v[212:213]
	v_pk_fma_f32 v[30:31], v[30:31], v[122:123], v[248:249]
	v_pk_fma_f32 v[40:41], v[40:41], v[128:129], v[226:227]
	v_pk_fma_f32 v[32:33], v[32:33], v[124:125], v[228:229]
	v_cvt_pk_bf16_f32 v226, v38, v39
	v_cvt_pk_bf16_f32 v227, v40, v41
	v_cvt_pk_bf16_f32 v228, v30, v31
	v_cvt_pk_bf16_f32 v229, v32, v33
	global_store_dwordx4 v[174:175], v[226:229], off offset:256
	s_mov_b32 s20, 0x50000
	s_mov_b32 s21, 0
	v_lshl_add_u64 v[174:175], v[172:173], 0, s[20:21]
	s_waitcnt vmcnt(14)
	v_lshlrev_b32_e32 v212, 16, v230
	v_and_b32_e32 v213, 0xffff0000, v230
	v_lshlrev_b32_e32 v248, 16, v232
	v_and_b32_e32 v249, 0xffff0000, v232
	v_lshlrev_b32_e32 v230, 16, v231
	v_and_b32_e32 v231, 0xffff0000, v231
	v_lshlrev_b32_e32 v232, 16, v233
	v_and_b32_e32 v233, 0xffff0000, v233
	v_pk_fma_f32 v[34:35], v[34:35], v[134:135], v[212:213]
	v_pk_fma_f32 v[26:27], v[26:27], v[130:131], v[248:249]
	v_pk_fma_f32 v[36:37], v[36:37], v[136:137], v[230:231]
	v_pk_fma_f32 v[28:29], v[28:29], v[132:133], v[232:233]
	v_cvt_pk_bf16_f32 v230, v34, v35
	v_cvt_pk_bf16_f32 v231, v36, v37
	v_cvt_pk_bf16_f32 v232, v26, v27
	v_cvt_pk_bf16_f32 v233, v28, v29
	global_store_dwordx4 v[174:175], v[230:233], off
	v_lshlrev_b32_e32 v212, 16, v234
	v_and_b32_e32 v213, 0xffff0000, v234
	v_lshlrev_b32_e32 v248, 16, v236
	v_and_b32_e32 v249, 0xffff0000, v236
	v_lshlrev_b32_e32 v234, 16, v235
	v_and_b32_e32 v235, 0xffff0000, v235
	v_lshlrev_b32_e32 v236, 16, v237
	v_and_b32_e32 v237, 0xffff0000, v237
	v_pk_fma_f32 v[18:19], v[18:19], v[126:127], v[212:213]
	v_pk_fma_f32 v[14:15], v[14:15], v[122:123], v[248:249]
	v_pk_fma_f32 v[20:21], v[20:21], v[128:129], v[234:235]
	v_pk_fma_f32 v[16:17], v[16:17], v[124:125], v[236:237]
	v_cvt_pk_bf16_f32 v234, v18, v19
	v_cvt_pk_bf16_f32 v235, v20, v21
	v_cvt_pk_bf16_f32 v236, v14, v15
	v_cvt_pk_bf16_f32 v237, v16, v17
	global_store_dwordx4 v[174:175], v[234:237], off offset:256
	s_mov_b32 s20, 0x58000
	s_mov_b32 s21, 0
	v_lshl_add_u64 v[174:175], v[172:173], 0, s[20:21]
	s_waitcnt vmcnt(14)
	v_lshlrev_b32_e32 v212, 16, v240
	v_and_b32_e32 v213, 0xffff0000, v240
	v_lshlrev_b32_e32 v248, 16, v242
	v_and_b32_e32 v249, 0xffff0000, v242
	v_lshlrev_b32_e32 v240, 16, v241
	v_and_b32_e32 v241, 0xffff0000, v241
	v_lshlrev_b32_e32 v242, 16, v243
	v_and_b32_e32 v243, 0xffff0000, v243
	v_pk_fma_f32 v[22:23], v[22:23], v[134:135], v[212:213]
	v_pk_fma_f32 v[10:11], v[10:11], v[130:131], v[248:249]
	v_pk_fma_f32 v[24:25], v[24:25], v[136:137], v[240:241]
	v_pk_fma_f32 v[12:13], v[12:13], v[132:133], v[242:243]
	v_cvt_pk_bf16_f32 v240, v22, v23
	v_cvt_pk_bf16_f32 v241, v24, v25
	v_cvt_pk_bf16_f32 v242, v10, v11
	v_cvt_pk_bf16_f32 v243, v12, v13
	global_store_dwordx4 v[174:175], v[240:243], off
	v_lshlrev_b32_e32 v212, 16, v244
	v_and_b32_e32 v213, 0xffff0000, v244
	v_lshlrev_b32_e32 v248, 16, v246
	v_and_b32_e32 v249, 0xffff0000, v246
	v_lshlrev_b32_e32 v244, 16, v245
	v_and_b32_e32 v245, 0xffff0000, v245
	v_lshlrev_b32_e32 v246, 16, v247
	v_and_b32_e32 v247, 0xffff0000, v247
	v_pk_fma_f32 v[6:7], v[6:7], v[126:127], v[212:213]
	v_pk_fma_f32 v[2:3], v[2:3], v[122:123], v[248:249]
	v_pk_fma_f32 v[8:9], v[8:9], v[128:129], v[244:245]
	v_pk_fma_f32 v[4:5], v[4:5], v[124:125], v[246:247]
	v_cvt_pk_bf16_f32 v244, v6, v7
	v_cvt_pk_bf16_f32 v245, v8, v9
	v_cvt_pk_bf16_f32 v246, v2, v3
	v_cvt_pk_bf16_f32 v247, v4, v5
	global_store_dwordx4 v[174:175], v[244:247], off offset:256
	s_andn2_b64 vcc, exec, s[0:1]
	s_mov_b64 s[0:1], -1
	s_movk_i32 s60, 0xe400
	s_mov_b32 s98, 1
	s_cbranch_vccnz .LBB0_373
	s_andn2_b64 vcc, exec, s[4:5]
	s_cbranch_vccnz .LBB0_372
	s_barrier
	s_branch .LBB0_372

.LBB0_398:
	v_lshl_add_u64 v[50:51], s[2:3], 0, v[178:179]
	s_add_i32 s11, s6, s7
	s_add_i32 s22, s11, 3
	s_ashr_i32 s23, s22, 31
	s_lshl_b64 s[24:25], s[22:23], 11
	s_lshl_b64 s[38:39], s[22:23], 12
	s_and_b64 vcc, exec, s[8:9]
	s_cbranch_vccz .Ln1_f32
	v_add_co_u32_e32 v18, vcc, 0x5c00000, v50
	v_lshl_add_u64 v[52:53], v[168:169], 0, s[24:25]
	s_nop 0
	v_addc_co_u32_e32 v19, vcc, 0, v51, vcc
	global_load_dwordx2 v[20:21], v[18:19], off
	global_load_dwordx2 v[24:25], v[18:19], off offset:512
	global_load_dwordx2 v[28:29], v[18:19], off offset:1024
	global_load_dwordx2 v[32:33], v[18:19], off offset:1536
	global_load_dwordx2 v[36:37], v[52:53], off
	global_load_dwordx2 v[40:41], v[52:53], off offset:512
	global_load_dwordx2 v[44:45], v[52:53], off offset:1024
	global_load_dwordx2 v[48:49], v[52:53], off offset:1536
	s_waitcnt vmcnt(0)
	v_lshlrev_b32_e32 v18, 16, v20
	v_and_b32_e32 v19, 0xffff0000, v20
	v_lshlrev_b32_e32 v20, 16, v21
	v_and_b32_e32 v21, 0xffff0000, v21
	v_lshlrev_b32_e32 v22, 16, v24
	v_and_b32_e32 v23, 0xffff0000, v24
	v_lshlrev_b32_e32 v24, 16, v25
	v_and_b32_e32 v25, 0xffff0000, v25
	v_lshlrev_b32_e32 v26, 16, v28
	v_and_b32_e32 v27, 0xffff0000, v28
	v_lshlrev_b32_e32 v28, 16, v29
	v_and_b32_e32 v29, 0xffff0000, v29
	v_lshlrev_b32_e32 v30, 16, v32
	v_and_b32_e32 v31, 0xffff0000, v32
	v_lshlrev_b32_e32 v32, 16, v33
	v_and_b32_e32 v33, 0xffff0000, v33
	v_lshlrev_b32_e32 v34, 16, v36
	v_and_b32_e32 v35, 0xffff0000, v36
	v_lshlrev_b32_e32 v36, 16, v37
	v_and_b32_e32 v37, 0xffff0000, v37
	v_lshlrev_b32_e32 v38, 16, v40
	v_and_b32_e32 v39, 0xffff0000, v40
	v_lshlrev_b32_e32 v40, 16, v41
	v_and_b32_e32 v41, 0xffff0000, v41
	v_lshlrev_b32_e32 v42, 16, v44
	v_and_b32_e32 v43, 0xffff0000, v44
	v_lshlrev_b32_e32 v44, 16, v45
	v_and_b32_e32 v45, 0xffff0000, v45
	v_lshlrev_b32_e32 v46, 16, v48
	v_and_b32_e32 v47, 0xffff0000, v48
	v_lshlrev_b32_e32 v48, 16, v49
	v_and_b32_e32 v49, 0xffff0000, v49
	s_branch .Ln1_loaded
.Ln1_f32:
	v_lshl_add_u64 v[54:55], v[166:167], 0, s[38:39]
	global_load_dwordx4 v[18:21], v[176:177], off
	global_load_dwordx4 v[22:25], v[176:177], off offset:1024
	global_load_dwordx4 v[26:29], v[176:177], off offset:2048
	global_load_dwordx4 v[30:33], v[176:177], off offset:3072
	global_load_dwordx4 v[34:37], v[54:55], off
	global_load_dwordx4 v[38:41], v[54:55], off offset:1024
	global_load_dwordx4 v[42:45], v[54:55], off offset:2048
	global_load_dwordx4 v[46:49], v[54:55], off offset:3072
	s_waitcnt vmcnt(0)
.Ln1_loaded:
	v_mul_f32_e32 v0, v35, v35
	v_mul_f32_e32 v52, v37, v37
	v_fmac_f32_e32 v0, v34, v34
	v_fmac_f32_e32 v52, v36, v36
	v_add_f32_e32 v0, v0, v52
	v_mul_f32_e32 v52, v39, v39
	v_mul_f32_e32 v53, v41, v41
	v_fmac_f32_e32 v52, v38, v38
	v_fmac_f32_e32 v53, v40, v40
	v_add_f32_e32 v52, v52, v53
	v_add_f32_e32 v0, v0, v52
	v_mul_f32_e32 v52, v43, v43
	v_mul_f32_e32 v53, v45, v45
	v_fmac_f32_e32 v52, v42, v42
	v_fmac_f32_e32 v53, v44, v44
	v_add_f32_e32 v52, v52, v53
	v_add_f32_e32 v0, v0, v52
	v_mul_f32_e32 v52, v19, v19
	v_mul_f32_e32 v53, v21, v21
	v_fmac_f32_e32 v52, v18, v18
	v_fmac_f32_e32 v53, v20, v20
	v_add_f32_e32 v52, v52, v53
	v_mul_f32_e32 v53, v23, v23
	v_mul_f32_e32 v54, v25, v25
	v_fmac_f32_e32 v53, v22, v22
	v_fmac_f32_e32 v54, v24, v24
	v_add_f32_e32 v53, v53, v54
	v_add_f32_e32 v52, v52, v53
	v_mul_f32_e32 v53, v27, v27
	v_mul_f32_e32 v54, v29, v29
	v_fmac_f32_e32 v53, v26, v26
	v_fmac_f32_e32 v54, v28, v28
	v_add_f32_e32 v53, v53, v54
	v_add_f32_e32 v52, v52, v53
	v_mul_f32_e32 v53, v31, v31
	v_mul_f32_e32 v54, v33, v33
	v_fmac_f32_e32 v53, v30, v30
	v_fmac_f32_e32 v54, v32, v32
	v_add_f32_e32 v53, v53, v54
	v_add_f32_e32 v58, v52, v53
	v_pk_mul_f32 v[52:53], v[48:49], v[48:49]
	v_pk_mul_f32 v[54:55], v[46:47], v[46:47]
	s_nop 0
	v_pk_mov_b32 v[56:57], v[54:55], v[52:53] op_sel:[1,0]
	v_mov_b32_e32 v55, v53
	v_pk_add_f32 v[52:53], v[56:57], v[54:55]
	s_nop 0
	v_add_f32_e32 v52, v52, v53
	v_add_f32_e32 v0, v0, v52
	v_mov_b32_e32 v53, v1
	v_add_f32_dpp v52, v58, v58 quad_perm:[1,0,3,2] row_mask:0xf bank_mask:0xf bound_ctrl:1
	v_add_f32_dpp v0, v0, v0 quad_perm:[1,0,3,2] row_mask:0xf bank_mask:0xf bound_ctrl:1
	s_nop 0
	v_add_f32_dpp v52, v52, v52 quad_perm:[2,3,0,1] row_mask:0xf bank_mask:0xf bound_ctrl:1
	v_add_f32_dpp v0, v0, v0 quad_perm:[2,3,0,1] row_mask:0xf bank_mask:0xf bound_ctrl:1
	s_nop 0
	v_add_f32_dpp v52, v52, v52 row_half_mirror row_mask:0xf bank_mask:0xf bound_ctrl:1
	v_add_f32_dpp v0, v0, v0 row_half_mirror row_mask:0xf bank_mask:0xf bound_ctrl:1
	s_nop 0
	v_add_f32_dpp v52, v52, v52 row_mirror row_mask:0xf bank_mask:0xf bound_ctrl:1
	v_add_f32_dpp v0, v0, v0 row_mirror row_mask:0xf bank_mask:0xf bound_ctrl:1
	s_nop 0
	v_mov_b32_dpp v53, v52 row_bcast:15 row_mask:0xa bank_mask:0xf
	v_add_f32_e32 v52, v52, v53
	v_mov_b32_e32 v53, v1
	s_nop 1
	v_mov_b32_dpp v53, v52 row_bcast:31 row_mask:0xc bank_mask:0xf
	v_add_f32_e32 v52, v52, v53
	s_nop 0
	v_readlane_b32 s0, v52, 63
	s_nop 1
	v_fma_f32 v52, s0, v217, v214
	v_mul_f32_e32 v53, 0x4b800000, v52
	v_cmp_gt_f32_e32 vcc, s33, v52
	s_nop 1
	v_cndmask_b32_e32 v52, v52, v53, vcc
	v_mov_b32_e32 v53, v1
	v_rsq_f32_e32 v52, v52
	s_nop 0
	v_mov_b32_dpp v53, v0 row_bcast:15 row_mask:0xa bank_mask:0xf
	v_add_f32_e32 v0, v0, v53
	v_mov_b32_e32 v53, v1
	s_nop 1
	v_mov_b32_dpp v53, v0 row_bcast:31 row_mask:0xc bank_mask:0xf
	v_add_f32_e32 v0, v0, v53
	s_nop 0
	v_readlane_b32 s0, v0, 63
	s_nop 1
	v_fma_f32 v0, s0, v217, v214
	v_mul_f32_e32 v53, 0x4b800000, v0
	v_cmp_gt_f32_e64 s[0:1], s33, v0
	s_nop 1
	v_cndmask_b32_e64 v0, v0, v53, s[0:1]
	v_rsq_f32_e32 v53, v0
	v_mul_f32_e32 v0, 0x45800000, v52
	v_cndmask_b32_e32 v0, v52, v0, vcc
	v_pk_mul_f32 v[20:21], v[0:1], v[20:21] op_sel_hi:[0,1]
	v_pk_mul_f32 v[18:19], v[0:1], v[18:19] op_sel_hi:[0,1]
	v_pk_fma_f32 v[58:59], v[180:181], v[20:21], v[4:5]
	v_pk_mul_f32 v[20:21], v[0:1], v[24:25] op_sel_hi:[0,1]
	v_mul_f32_e32 v52, 0x45800000, v53
	v_pk_fma_f32 v[54:55], v[182:183], v[18:19], v[2:3]
	v_pk_mul_f32 v[18:19], v[0:1], v[22:23] op_sel_hi:[0,1]
	v_pk_fma_f32 v[90:91], v[184:185], v[20:21], v[8:9]
	v_pk_mul_f32 v[20:21], v[0:1], v[28:29] op_sel_hi:[0,1]
	v_cndmask_b32_e64 v52, v53, v52, s[0:1]
	v_pk_fma_f32 v[74:75], v[186:187], v[18:19], v[6:7]
	v_pk_mul_f32 v[18:19], v[0:1], v[26:27] op_sel_hi:[0,1]
	v_pk_fma_f32 v[122:123], v[188:189], v[20:21], v[12:13]
	v_pk_mul_f32 v[20:21], v[0:1], v[32:33] op_sel_hi:[0,1]
	s_mov_b32 s0, 0x1c00000
	v_pk_fma_f32 v[106:107], v[190:191], v[18:19], v[10:11]
	v_pk_mul_f32 v[18:19], v[0:1], v[30:31] op_sel_hi:[0,1]
	v_pk_fma_f32 v[212:213], v[192:193], v[20:21], v[16:17]
	v_add_co_u32_e32 v20, vcc, s0, v50
	v_pk_fma_f32 v[134:135], v[194:195], v[18:19], v[14:15]
	v_cvt_pk_bf16_f32 v18, v54, v55
	v_cvt_pk_bf16_f32 v19, v58, v59
	v_addc_co_u32_e32 v21, vcc, 0, v51, vcc
	flat_store_dwordx2 v[20:21], v[18:19]
	v_cvt_pk_bf16_f32 v18, v74, v75
	v_cvt_pk_bf16_f32 v19, v90, v91
	flat_store_dwordx2 v[20:21], v[18:19] offset:512
	v_cvt_pk_bf16_f32 v18, v106, v107
	v_cvt_pk_bf16_f32 v19, v122, v123
	flat_store_dwordx2 v[20:21], v[18:19] offset:1024
	v_cvt_pk_bf16_f32 v18, v134, v135
	v_cvt_pk_bf16_f32 v19, v212, v213
	flat_store_dwordx2 v[20:21], v[18:19] offset:1536
	v_pk_mul_f32 v[18:19], v[52:53], v[34:35] op_sel_hi:[0,1]
	v_pk_mul_f32 v[20:21], v[52:53], v[36:37] op_sel_hi:[0,1]
	v_pk_fma_f32 v[208:209], v[180:181], v[20:21], v[4:5]
	v_pk_fma_f32 v[210:211], v[182:183], v[18:19], v[2:3]
	v_pk_mul_f32 v[18:19], v[52:53], v[38:39] op_sel_hi:[0,1]
	v_pk_mul_f32 v[20:21], v[52:53], v[40:41] op_sel_hi:[0,1]
	v_pk_fma_f32 v[204:205], v[184:185], v[20:21], v[8:9]
	v_pk_fma_f32 v[206:207], v[186:187], v[18:19], v[6:7]
	v_pk_mul_f32 v[18:19], v[52:53], v[42:43] op_sel_hi:[0,1]
	v_pk_mul_f32 v[20:21], v[52:53], v[44:45] op_sel_hi:[0,1]
	v_pk_fma_f32 v[200:201], v[188:189], v[20:21], v[12:13]
	v_pk_fma_f32 v[202:203], v[190:191], v[18:19], v[10:11]
	v_pk_mul_f32 v[18:19], v[52:53], v[46:47] op_sel_hi:[0,1]
	v_pk_mul_f32 v[20:21], v[52:53], v[48:49] op_sel_hi:[0,1]
	v_pk_fma_f32 v[196:197], v[192:193], v[20:21], v[16:17]
	v_pk_fma_f32 v[198:199], v[194:195], v[18:19], v[14:15]
	v_lshl_add_u64 v[18:19], v[170:171], 0, s[24:25]
	v_cvt_pk_bf16_f32 v20, v210, v211
	v_cvt_pk_bf16_f32 v21, v208, v209
	flat_store_dwordx2 v[18:19], v[20:21]
	v_cvt_pk_bf16_f32 v20, v206, v207
	v_cvt_pk_bf16_f32 v21, v204, v205
	flat_store_dwordx2 v[18:19], v[20:21] offset:512
	v_cvt_pk_bf16_f32 v20, v202, v203
	v_cvt_pk_bf16_f32 v21, v200, v201
	flat_store_dwordx2 v[18:19], v[20:21] offset:1024
	v_cvt_pk_bf16_f32 v20, v198, v199
	v_cvt_pk_bf16_f32 v21, v196, v197
	flat_store_dwordx2 v[18:19], v[20:21] offset:1536
	ds_read_b128 v[22:25], v159
	ds_read_b128 v[18:21], v159 offset:1024
	ds_read_b128 v[26:29], v159 offset:2048
	ds_read_b128 v[30:33], v159 offset:3072
	s_waitcnt lgkmcnt(0)
	v_pk_fma_f32 v[34:35], v[54:55], v[24:25], 0 op_sel_hi:[0,1,0]
	v_pk_fma_f32 v[38:39], v[54:55], v[22:23], 0 op_sel_hi:[0,1,0]
	v_pk_fma_f32 v[46:47], v[54:55], v[28:29], v[34:35] op_sel:[1,0,0]
	ds_read_b128 v[34:37], v159 offset:4096
	v_pk_fma_f32 v[40:41], v[54:55], v[20:21], 0 op_sel_hi:[0,1,0]
	v_pk_fma_f32 v[42:43], v[54:55], v[18:19], 0 op_sel_hi:[0,1,0]
	v_pk_fma_f32 v[44:45], v[54:55], v[26:27], v[38:39] op_sel:[1,0,0]
	v_pk_fma_f32 v[48:49], v[54:55], v[32:33], v[40:41] op_sel:[1,0,0]
	ds_read_b128 v[38:41], v159 offset:5120
	v_pk_fma_f32 v[50:51], v[54:55], v[30:31], v[42:43] op_sel:[1,0,0]
	s_waitcnt lgkmcnt(0)
	v_pk_fma_f32 v[54:55], v[58:59], v[34:35], v[44:45] op_sel_hi:[0,1,1]
	ds_read_b128 v[42:45], v159 offset:6144
	v_pk_fma_f32 v[52:53], v[58:59], v[36:37], v[46:47] op_sel_hi:[0,1,1]
	v_pk_fma_f32 v[62:63], v[58:59], v[40:41], v[48:49] op_sel_hi:[0,1,1]
	ds_read_b128 v[46:49], v159 offset:7168
	v_pk_fma_f32 v[60:61], v[58:59], v[38:39], v[50:51] op_sel_hi:[0,1,1]
	s_waitcnt lgkmcnt(0)
	v_pk_fma_f32 v[64:65], v[58:59], v[44:45], v[52:53] op_sel:[1,0,0]
	ds_read_b128 v[50:53], v159 offset:8192
	v_pk_fma_f32 v[66:67], v[58:59], v[42:43], v[54:55] op_sel:[1,0,0]
	ds_read_b128 v[54:57], v159 offset:9216
	v_pk_fma_f32 v[68:69], v[58:59], v[48:49], v[62:63] op_sel:[1,0,0]
	v_pk_fma_f32 v[62:63], v[58:59], v[46:47], v[60:61] op_sel:[1,0,0]
	ds_read_b128 v[58:61], v159 offset:10240
	s_waitcnt lgkmcnt(0)
	v_pk_fma_f32 v[70:71], v[74:75], v[50:51], v[66:67] op_sel_hi:[0,1,1]
	v_pk_fma_f32 v[66:67], v[74:75], v[52:53], v[64:65] op_sel_hi:[0,1,1]
	v_pk_fma_f32 v[76:77], v[74:75], v[54:55], v[62:63] op_sel_hi:[0,1,1]
	ds_read_b128 v[62:65], v159 offset:11264
	v_pk_fma_f32 v[72:73], v[74:75], v[56:57], v[68:69] op_sel_hi:[0,1,1]
	v_pk_fma_f32 v[78:79], v[74:75], v[60:61], v[66:67] op_sel:[1,0,0]
	ds_read_b128 v[66:69], v159 offset:12288
	v_pk_fma_f32 v[80:81], v[74:75], v[58:59], v[70:71] op_sel:[1,0,0]
	s_waitcnt lgkmcnt(0)
	v_pk_fma_f32 v[82:83], v[74:75], v[64:65], v[72:73] op_sel:[1,0,0]
	ds_read_b128 v[70:73], v159 offset:13312
	v_pk_fma_f32 v[84:85], v[74:75], v[62:63], v[76:77] op_sel:[1,0,0]
	ds_read_b128 v[74:77], v159 offset:14336
	v_pk_fma_f32 v[86:87], v[90:91], v[66:67], v[80:81] op_sel_hi:[0,1,1]
	v_pk_fma_f32 v[88:89], v[90:91], v[68:69], v[78:79] op_sel_hi:[0,1,1]
	ds_read_b128 v[78:81], v159 offset:15360
	s_waitcnt lgkmcnt(0)
	v_pk_fma_f32 v[92:93], v[90:91], v[70:71], v[84:85] op_sel_hi:[0,1,1]
	v_pk_fma_f32 v[94:95], v[90:91], v[72:73], v[82:83] op_sel_hi:[0,1,1]
	v_pk_fma_f32 v[96:97], v[90:91], v[76:77], v[88:89] op_sel:[1,0,0]
	ds_read_b128 v[82:85], v159 offset:16384
	v_pk_fma_f32 v[98:99], v[90:91], v[74:75], v[86:87] op_sel:[1,0,0]
	ds_read_b128 v[86:89], v159 offset:17408
	v_pk_fma_f32 v[100:101], v[90:91], v[80:81], v[94:95] op_sel:[1,0,0]
	v_pk_fma_f32 v[94:95], v[90:91], v[78:79], v[92:93] op_sel:[1,0,0]
	ds_read_b128 v[90:93], v159 offset:18432
	s_waitcnt lgkmcnt(0)
	v_pk_fma_f32 v[102:103], v[106:107], v[82:83], v[98:99] op_sel_hi:[0,1,1]
	v_pk_fma_f32 v[98:99], v[106:107], v[84:85], v[96:97] op_sel_hi:[0,1,1]
	v_pk_fma_f32 v[108:109], v[106:107], v[86:87], v[94:95] op_sel_hi:[0,1,1]
	ds_read_b128 v[94:97], v159 offset:19456
	v_pk_fma_f32 v[104:105], v[106:107], v[88:89], v[100:101] op_sel_hi:[0,1,1]
	v_pk_fma_f32 v[110:111], v[106:107], v[92:93], v[98:99] op_sel:[1,0,0]
	ds_read_b128 v[98:101], v159 offset:20480
	v_pk_fma_f32 v[112:113], v[106:107], v[90:91], v[102:103] op_sel:[1,0,0]
	s_waitcnt lgkmcnt(0)
	v_pk_fma_f32 v[114:115], v[106:107], v[96:97], v[104:105] op_sel:[1,0,0]
	ds_read_b128 v[102:105], v159 offset:21504
	v_pk_fma_f32 v[116:117], v[106:107], v[94:95], v[108:109] op_sel:[1,0,0]
	ds_read_b128 v[106:109], v159 offset:22528
	v_pk_fma_f32 v[118:119], v[122:123], v[98:99], v[112:113] op_sel_hi:[0,1,1]
	v_pk_fma_f32 v[120:121], v[122:123], v[100:101], v[110:111] op_sel_hi:[0,1,1]
	ds_read_b128 v[110:113], v159 offset:23552
	s_waitcnt lgkmcnt(0)
	v_pk_fma_f32 v[124:125], v[122:123], v[102:103], v[116:117] op_sel_hi:[0,1,1]
	v_pk_fma_f32 v[126:127], v[122:123], v[104:105], v[114:115] op_sel_hi:[0,1,1]
	v_pk_fma_f32 v[128:129], v[122:123], v[108:109], v[120:121] op_sel:[1,0,0]
	ds_read_b128 v[114:117], v159 offset:24576
	v_pk_fma_f32 v[130:131], v[122:123], v[106:107], v[118:119] op_sel:[1,0,0]
	ds_read_b128 v[118:121], v159 offset:25600
	v_pk_fma_f32 v[132:133], v[122:123], v[112:113], v[126:127] op_sel:[1,0,0]
	v_pk_fma_f32 v[126:127], v[122:123], v[110:111], v[124:125] op_sel:[1,0,0]
	ds_read_b128 v[122:125], v159 offset:26624
	s_waitcnt lgkmcnt(0)
	v_pk_fma_f32 v[136:137], v[134:135], v[114:115], v[130:131] op_sel_hi:[0,1,1]
	v_pk_fma_f32 v[130:131], v[134:135], v[116:117], v[128:129] op_sel_hi:[0,1,1]
	v_pk_fma_f32 v[138:139], v[134:135], v[118:119], v[126:127] op_sel_hi:[0,1,1]
	ds_read_b128 v[126:129], v159 offset:27648
	v_pk_fma_f32 v[140:141], v[134:135], v[120:121], v[132:133] op_sel_hi:[0,1,1]
	v_pk_fma_f32 v[142:143], v[134:135], v[124:125], v[130:131] op_sel:[1,0,0]
	ds_read_b128 v[130:133], v159 offset:28672
	v_pk_fma_f32 v[144:145], v[134:135], v[122:123], v[136:137] op_sel:[1,0,0]
	s_waitcnt lgkmcnt(0)
	v_pk_fma_f32 v[146:147], v[134:135], v[128:129], v[140:141] op_sel:[1,0,0]
	v_pk_fma_f32 v[148:149], v[134:135], v[126:127], v[138:139] op_sel:[1,0,0]
	ds_read_b128 v[138:141], v159 offset:30720
	ds_read_b128 v[134:137], v159 offset:29696
	v_pk_fma_f32 v[154:155], v[212:213], v[130:131], v[144:145] op_sel_hi:[0,1,1]
	v_pk_fma_f32 v[156:157], v[212:213], v[132:133], v[142:143] op_sel_hi:[0,1,1]
	ds_read_b128 v[142:145], v159 offset:31744
	s_waitcnt lgkmcnt(0)
	v_pk_fma_f32 v[154:155], v[212:213], v[138:139], v[154:155] op_sel:[1,0,0]
	v_pk_fma_f32 v[148:149], v[212:213], v[134:135], v[148:149] op_sel_hi:[0,1,1]
	v_pk_fma_f32 v[156:157], v[212:213], v[140:141], v[156:157] op_sel:[1,0,0]
	v_add_f32_dpp v0, v154, v154 quad_perm:[1,0,3,2] row_mask:0xf bank_mask:0xf bound_ctrl:1
	v_mov_b32_e32 v154, v1
	v_pk_fma_f32 v[148:149], v[212:213], v[142:143], v[148:149] op_sel:[1,0,0]
	v_add_f32_dpp v0, v0, v0 quad_perm:[2,3,0,1] row_mask:0xf bank_mask:0xf bound_ctrl:1
	v_pk_fma_f32 v[146:147], v[212:213], v[136:137], v[146:147] op_sel_hi:[0,1,1]
	v_pk_fma_f32 v[146:147], v[212:213], v[144:145], v[146:147] op_sel:[1,0,0]
	v_add_f32_dpp v0, v0, v0 row_half_mirror row_mask:0xf bank_mask:0xf bound_ctrl:1
	s_nop 1
	v_add_f32_dpp v0, v0, v0 row_mirror row_mask:0xf bank_mask:0xf bound_ctrl:1
	s_nop 1
	v_mov_b32_dpp v154, v0 row_bcast:15 row_mask:0xa bank_mask:0xf
	v_add_f32_e32 v0, v0, v154
	v_mov_b32_e32 v154, v1
	s_nop 1
	v_mov_b32_dpp v154, v0 row_bcast:31 row_mask:0xc bank_mask:0xf
	v_add_f32_e32 v0, v0, v154
	s_nop 0
	v_readlane_b32 s24, v0, 63
	v_add_f32_dpp v0, v148, v148 quad_perm:[1,0,3,2] row_mask:0xf bank_mask:0xf bound_ctrl:1
	v_mov_b32_e32 v148, v1
	s_nop 0
	v_add_f32_dpp v0, v0, v0 quad_perm:[2,3,0,1] row_mask:0xf bank_mask:0xf bound_ctrl:1
	s_nop 1
	v_add_f32_dpp v0, v0, v0 row_half_mirror row_mask:0xf bank_mask:0xf bound_ctrl:1
	s_nop 1
	v_add_f32_dpp v0, v0, v0 row_mirror row_mask:0xf bank_mask:0xf bound_ctrl:1
	s_nop 1
	v_mov_b32_dpp v148, v0 row_bcast:15 row_mask:0xa bank_mask:0xf
	v_add_f32_e32 v0, v0, v148
	v_mov_b32_e32 v148, v1
	s_nop 1
	v_mov_b32_dpp v148, v0 row_bcast:31 row_mask:0xc bank_mask:0xf
	v_add_f32_e32 v0, v0, v148
	v_mov_b32_e32 v148, v1
	v_readlane_b32 s11, v0, 63
	v_add_f32_dpp v0, v155, v155 quad_perm:[1,0,3,2] row_mask:0xf bank_mask:0xf bound_ctrl:1
	s_nop 1
	v_add_f32_dpp v0, v0, v0 quad_perm:[2,3,0,1] row_mask:0xf bank_mask:0xf bound_ctrl:1
	s_nop 1
	v_add_f32_dpp v0, v0, v0 row_half_mirror row_mask:0xf bank_mask:0xf bound_ctrl:1
	s_nop 1
	v_add_f32_dpp v0, v0, v0 row_mirror row_mask:0xf bank_mask:0xf bound_ctrl:1
	s_nop 1
	v_mov_b32_dpp v148, v0 row_bcast:15 row_mask:0xa bank_mask:0xf
	v_add_f32_e32 v0, v0, v148
	v_mov_b32_e32 v148, v1
	s_nop 1
	v_mov_b32_dpp v148, v0 row_bcast:31 row_mask:0xc bank_mask:0xf
	v_add_f32_e32 v0, v0, v148
	v_mov_b32_e32 v148, v1
	v_readlane_b32 s26, v0, 63
	v_add_f32_dpp v0, v149, v149 quad_perm:[1,0,3,2] row_mask:0xf bank_mask:0xf bound_ctrl:1
	s_nop 1
	v_add_f32_dpp v0, v0, v0 quad_perm:[2,3,0,1] row_mask:0xf bank_mask:0xf bound_ctrl:1
	s_nop 1
	v_add_f32_dpp v0, v0, v0 row_half_mirror row_mask:0xf bank_mask:0xf bound_ctrl:1
	s_nop 1
	v_add_f32_dpp v0, v0, v0 row_mirror row_mask:0xf bank_mask:0xf bound_ctrl:1
	s_nop 1
	v_mov_b32_dpp v148, v0 row_bcast:15 row_mask:0xa bank_mask:0xf
	v_add_f32_e32 v0, v0, v148
	v_mov_b32_e32 v148, v1
	s_nop 1
	v_mov_b32_dpp v148, v0 row_bcast:31 row_mask:0xc bank_mask:0xf
	v_add_f32_e32 v0, v0, v148
	v_mov_b32_e32 v148, v1
	v_readlane_b32 s25, v0, 63
	v_add_f32_dpp v0, v156, v156 quad_perm:[1,0,3,2] row_mask:0xf bank_mask:0xf bound_ctrl:1
	s_nop 1
	v_add_f32_dpp v0, v0, v0 quad_perm:[2,3,0,1] row_mask:0xf bank_mask:0xf bound_ctrl:1
	s_nop 1
	v_add_f32_dpp v0, v0, v0 row_half_mirror row_mask:0xf bank_mask:0xf bound_ctrl:1
	s_nop 1
	v_add_f32_dpp v0, v0, v0 row_mirror row_mask:0xf bank_mask:0xf bound_ctrl:1
	s_nop 1
	v_mov_b32_dpp v148, v0 row_bcast:15 row_mask:0xa bank_mask:0xf
	v_add_f32_e32 v0, v0, v148
	v_mov_b32_e32 v148, v1
	s_nop 1
	v_mov_b32_dpp v148, v0 row_bcast:31 row_mask:0xc bank_mask:0xf
	v_add_f32_e32 v0, v0, v148
	s_nop 0
	v_readlane_b32 s31, v0, 63
	v_add_f32_dpp v0, v146, v146 quad_perm:[1,0,3,2] row_mask:0xf bank_mask:0xf bound_ctrl:1
	v_mov_b32_e32 v146, v1
	s_nop 0
	v_add_f32_dpp v0, v0, v0 quad_perm:[2,3,0,1] row_mask:0xf bank_mask:0xf bound_ctrl:1
	s_nop 1
	v_add_f32_dpp v0, v0, v0 row_half_mirror row_mask:0xf bank_mask:0xf bound_ctrl:1
	s_nop 1
	v_add_f32_dpp v0, v0, v0 row_mirror row_mask:0xf bank_mask:0xf bound_ctrl:1
	s_nop 1
	v_mov_b32_dpp v146, v0 row_bcast:15 row_mask:0xa bank_mask:0xf
	v_add_f32_e32 v0, v0, v146
	v_mov_b32_e32 v146, v1
	s_nop 1
	v_mov_b32_dpp v146, v0 row_bcast:31 row_mask:0xc bank_mask:0xf
	v_add_f32_e32 v0, v0, v146
	v_mov_b32_e32 v146, v1
	v_readlane_b32 s27, v0, 63
	v_add_f32_dpp v0, v157, v157 quad_perm:[1,0,3,2] row_mask:0xf bank_mask:0xf bound_ctrl:1
	s_nop 1
	v_add_f32_dpp v0, v0, v0 quad_perm:[2,3,0,1] row_mask:0xf bank_mask:0xf bound_ctrl:1
	s_nop 1
	v_add_f32_dpp v0, v0, v0 row_half_mirror row_mask:0xf bank_mask:0xf bound_ctrl:1
	s_nop 1
	v_add_f32_dpp v0, v0, v0 row_mirror row_mask:0xf bank_mask:0xf bound_ctrl:1
	s_nop 1
	v_mov_b32_dpp v146, v0 row_bcast:15 row_mask:0xa bank_mask:0xf
	v_add_f32_e32 v0, v0, v146
	v_mov_b32_e32 v146, v1
	s_nop 1
	v_mov_b32_dpp v146, v0 row_bcast:31 row_mask:0xc bank_mask:0xf
	v_add_f32_e32 v0, v0, v146
	v_mov_b32_e32 v146, v1
	v_readlane_b32 s38, v0, 63
	v_add_f32_dpp v0, v147, v147 quad_perm:[1,0,3,2] row_mask:0xf bank_mask:0xf bound_ctrl:1
	s_nop 1
	v_add_f32_dpp v0, v0, v0 quad_perm:[2,3,0,1] row_mask:0xf bank_mask:0xf bound_ctrl:1
	s_nop 1
	v_add_f32_dpp v0, v0, v0 row_half_mirror row_mask:0xf bank_mask:0xf bound_ctrl:1
	s_nop 1
	v_add_f32_dpp v0, v0, v0 row_mirror row_mask:0xf bank_mask:0xf bound_ctrl:1
	s_nop 1
	v_mov_b32_dpp v146, v0 row_bcast:15 row_mask:0xa bank_mask:0xf
	v_add_f32_e32 v0, v0, v146
	v_mov_b32_e32 v146, v1
	s_nop 1
	v_mov_b32_dpp v146, v0 row_bcast:31 row_mask:0xc bank_mask:0xf
	v_add_f32_e32 v0, v0, v146
	s_nop 0
	v_readlane_b32 s37, v0, 63
	s_and_saveexec_b64 s[0:1], s[4:5]
	s_cbranch_execz .LBB0_432
	s_add_u32 s39, s2, s20
	s_addc_u32 s40, s3, s21
	v_mov_b32_e32 v0, s39
	v_add_co_u32_e32 v146, vcc, 0x200000, v0
	v_mov_b32_e32 v0, s40
	v_mov_b32_e32 v222, s24
	v_mov_b32_e32 v223, s26
	v_mov_b32_e32 v224, s31
	v_mov_b32_e32 v225, s38
	v_addc_co_u32_e32 v147, vcc, 0, v0, vcc
	flat_store_dwordx4 v[146:147], v[222:225]
	s_nop 1
	v_mov_b32_e32 v222, s11
	v_mov_b32_e32 v223, s25
	v_mov_b32_e32 v224, s27
	v_mov_b32_e32 v225, s37
	flat_store_dwordx4 v[146:147], v[222:225] offset:16
